# s5_fill rewritten by hand: wave owns whole rows of WE/WY, exp/sincos evaluated once per (group,state,distance) with the compiler's own instruction sequence, 16-byte stores
# baseline (speedup 1.0000x reference)
; DI int opqv(int x) { asm volatile("" : "+v"(x)); return x; }
; DI char* opq(char* p) { asm volatile("" : "+s"(p)); return p; }
; DI void sincos_(float x, float& sn, float& cs) { float s_, c_; sincosf(x, &s_, &c_); sn = s_; cs = c_; }
; DI void s5_fill(const Params& p, int j) {
;   const int tid = opqv(threadIdx.x), nb = gridDim.x, bid = blockIdx.x;
;   char* ws = opq(p.ws);
;   const float4* s5z = (const float4*)(ws + OFF_S5Z) + j * 2048; const float2* bbar = (const float2*)(ws + OFF_BBAR) + j * 2048 * 16;
;   const float* ktab = (const float*)(ws + OFF_KTAB) + (size_t)j * 32 * 32 * 256;
;   u16* WE = (u16*)(ws + OFF_WE); u16* WY = (u16*)(ws + OFF_WY);
;   for (int idx = bid * NTHR + tid; idx < 32 * 256 * 512; idx += nb * NTHR) {
;     const int g = idx >> 17, n2 = (idx >> 9) & 255, k = idx & 511, jj = k >> 4, q = k & 15, n = n2 & 63;
;     if (n2 >= 128) { WE[idx] = 0; continue; }
;     const float4 z = s5z[g * 64 + n];
;     const float d = (float)(31 - jj);
;     const float mg = expf(d * z.x), ang = d * z.y; float sn_, cs_; sincos_(ang, sn_, cs_);
;     const float er = mg * cs_, ei = mg * sn_;
;     const float2 bb = bbar[(g * 64 + n) * 16 + q];
;     const float v = (n2 < 64) ? (er * bb.x - ei * bb.y) : (er * bb.y + ei * bb.x);
;     WE[idx] = f2bf(v);
.LBB0_819:
	s_waitcnt vmcnt(0) lgkmcnt(0)
	v_readlane_b32 s10, v251, 13
	v_readlane_b32 s11, v251, 14
	v_readlane_b32 s85, v254, 25
	v_readlane_b32 s22, v253, 48
	v_readlane_b32 s23, v253, 50
	v_lshrrev_b32_e32 v0, 6, v182
	v_and_b32_e32 v8, 63, v182
	v_readfirstlane_b32 s20, v0
	s_lshl_b32 s0, s22, 3
	s_add_u32 s20, s20, s0
	s_lshl_b32 s35, s23, 3
	s_lshl_b32 s0, s85, 15
	s_add_u32 s8, s10, s0
	s_addc_u32 s9, s11, 0
	s_add_u32 s8, s8, 0xe34100
	s_addc_u32 s9, s9, 0
	s_lshl_b32 s0, s85, 18
	s_add_u32 s12, s10, s0
	s_addc_u32 s13, s11, 0
	s_add_u32 s12, s12, 0xe44100
	s_addc_u32 s13, s13, 0
	s_add_u32 s14, s10, 0x7004100
	s_addc_u32 s15, s11, 0
	s_lshl_b32 s0, s85, 20
	s_add_u32 s22, s10, s0
	s_addc_u32 s23, s11, 0
	s_add_u32 s22, s22, 0xec4100
	s_addc_u32 s23, s23, 0
	s_add_u32 s10, s10, 0x7804100
	s_addc_u32 s11, s11, 0
	s_lshl_b32 s0, s85, 17
	v_readlane_b32 s24, v254, 4
	v_readlane_b32 s25, v254, 5
	s_add_u32 s24, s24, s0
	s_addc_u32 s25, s25, 0
	v_readlane_b32 s28, v254, 6
	v_readlane_b32 s29, v254, 7
	s_add_u32 s28, s28, s0
	s_addc_u32 s29, s29, 0
	s_lshl_b32 s0, s85, 11
	v_readlane_b32 s76, v254, 8
	v_readlane_b32 s77, v254, 9
	s_add_u32 s76, s76, s0
	s_addc_u32 s77, s77, 0
	v_and_b32_e32 v9, 31, v8
	v_lshrrev_b32_e32 v10, 5, v8
	v_lshlrev_b32_e32 v11, 4, v8
	v_mov_b32_e32 v28, 0
	v_mov_b32_e32 v29, 0
	v_mov_b32_e32 v30, 0
	v_mov_b32_e32 v31, 0
	s_mov_b32 s34, s20
.Ls5f_z_loop:
	s_cmp_lt_u32 s34, 0x1000
	s_cbranch_scc0 .Ls5f_z_done
	s_lshr_b32 s0, s34, 7
	s_lshl_b32 s0, s0, 8
	s_and_b32 s1, s34, 0x7f
	s_add_u32 s0, s0, s1
	s_add_u32 s0, s0, 0x80
	s_lshl_b32 s0, s0, 10
	s_add_u32 s78, s14, s0
	s_addc_u32 s79, s15, 0
	global_store_dwordx4 v11, v[28:31], s[78:79]
	s_add_u32 s34, s34, s35
	s_branch .Ls5f_z_loop
.Ls5f_z_done:
	s_mov_b32 s34, s20
.Ls5f_e_loop:
	s_cmp_lt_u32 s34, 0x800
	s_cbranch_scc0 .Ls5f_e_done
	s_lshl_b32 s0, s34, 4
	s_add_u32 s0, s8, s0
	s_addc_u32 s1, s9, 0
	s_load_dwordx2 s[68:69], s[0:1], 0x0
	s_lshl_b32 s4, s34, 7
	s_add_u32 s4, s12, s4
	s_addc_u32 s5, s13, 0
	global_load_dwordx4 v[32:35], v161, s[4:5]
	global_load_dwordx4 v[36:39], v161, s[4:5] offset:16
	global_load_dwordx4 v[40:43], v161, s[4:5] offset:32
	global_load_dwordx4 v[44:47], v161, s[4:5] offset:48
	global_load_dwordx4 v[48:51], v161, s[4:5] offset:64
	global_load_dwordx4 v[52:55], v161, s[4:5] offset:80
	global_load_dwordx4 v[56:59], v161, s[4:5] offset:96
	global_load_dwordx4 v[60:63], v161, s[4:5] offset:112
	v_sub_u32_e32 v12, 31, v9
	v_cvt_f32_u32_e32 v12, v12
	s_waitcnt lgkmcnt(0)
	v_mov_b32_e32 v4, s68
	v_mov_b32_e32 v5, s69
	v_mul_f32_e32 v5, v5, v12
	v_and_b32_e32 v7, 0x7fffffff, v5
	s_brev_b32 s0, 18
	v_cmp_nlt_f32_e64 s[0:1], |v5|, s0
	s_and_saveexec_b64 s[4:5], s[0:1]
	s_xor_b64 s[30:31], exec, s[4:5]
	s_cbranch_execz .Ls5f_small1
	v_lshrrev_b32_e32 v13, 23, v7
	v_add_u32_e32 v13, 0xffffff88, v13
	v_cmp_lt_u32_e32 vcc, 63, v13
	s_mov_b32 s6, 0xfe5163ab
	s_nop 0
	v_cndmask_b32_e32 v14, 0, v192, vcc
	v_add_u32_e32 v13, v14, v13
	v_cmp_lt_u32_e64 s[0:1], 31, v13
	s_nop 1
	v_cndmask_b32_e64 v14, 0, v201, s[0:1]
	v_add_u32_e32 v13, v14, v13
	v_cmp_lt_u32_e64 s[4:5], 31, v13
	s_nop 1
	v_cndmask_b32_e64 v14, 0, v201, s[4:5]
	v_add_u32_e32 v13, v14, v13
	v_and_b32_e32 v14, 0x7fffff, v7
	v_or_b32_e32 v26, 0x800000, v14
	v_mad_u64_u32 v[14:15], s[6:7], v26, s6, 0
	v_mov_b32_e32 v160, v15
	s_mov_b32 s6, 0x3c439041
	v_mad_u64_u32 v[16:17], s[6:7], v26, s6, v[160:161]
	v_mov_b32_e32 v160, v17
	s_mov_b32 s6, 0xdb629599
	v_mad_u64_u32 v[18:19], s[6:7], v26, s6, v[160:161]
	v_mov_b32_e32 v160, v19
	s_mov_b32 s6, 0xf534ddc0
	v_mad_u64_u32 v[20:21], s[6:7], v26, s6, v[160:161]
	v_mov_b32_e32 v160, v21
	s_mov_b32 s6, 0xfc2757d1
	v_mad_u64_u32 v[22:23], s[6:7], v26, s6, v[160:161]
	v_mov_b32_e32 v160, v23
	s_mov_b32 s6, 0x4e441529
	v_mad_u64_u32 v[24:25], s[6:7], v26, s6, v[160:161]
	v_mov_b32_e32 v160, v25
	s_mov_b32 s6, 0xa2f9836e
	v_mad_u64_u32 v[26:27], s[6:7], v26, s6, v[160:161]
	v_cndmask_b32_e32 v15, v24, v20, vcc
	v_cndmask_b32_e32 v17, v26, v22, vcc
	v_cndmask_b32_e32 v21, v27, v24, vcc
	v_cndmask_b32_e64 v19, v17, v15, s[0:1]
	v_cndmask_b32_e64 v17, v21, v17, s[0:1]
	v_cndmask_b32_e32 v21, v22, v18, vcc
	v_cndmask_b32_e64 v15, v15, v21, s[0:1]
	v_sub_u32_e32 v22, 32, v13
	v_cmp_eq_u32_e64 s[6:7], 0, v13
	v_cndmask_b32_e32 v13, v20, v16, vcc
	v_cndmask_b32_e64 v17, v17, v19, s[4:5]
	v_cndmask_b32_e64 v19, v19, v15, s[4:5]
	v_cndmask_b32_e64 v16, v21, v13, s[0:1]
	v_alignbit_b32 v23, v17, v19, v22
	v_cndmask_b32_e64 v15, v15, v16, s[4:5]
	v_cndmask_b32_e64 v17, v23, v17, s[6:7]
	v_alignbit_b32 v20, v19, v15, v22
	v_cndmask_b32_e32 v14, v18, v14, vcc
	v_cndmask_b32_e64 v19, v20, v19, s[6:7]
	v_bfe_u32 v23, v17, 29, 1
	v_cndmask_b32_e64 v13, v13, v14, s[0:1]
	v_alignbit_b32 v20, v17, v19, 30
	v_sub_u32_e32 v24, 0, v23
	v_cndmask_b32_e64 v13, v16, v13, s[4:5]
	v_xor_b32_e32 v20, v20, v24
	v_alignbit_b32 v14, v15, v13, v22
	v_cndmask_b32_e64 v14, v14, v15, s[6:7]
	v_ffbh_u32_e32 v16, v20
	v_alignbit_b32 v15, v19, v14, 30
	v_min_u32_e32 v16, 32, v16
	v_alignbit_b32 v13, v14, v13, 30
	v_xor_b32_e32 v15, v15, v24
	v_sub_u32_e32 v18, 31, v16
	v_xor_b32_e32 v13, v13, v24
	v_alignbit_b32 v19, v20, v15, v18
	v_alignbit_b32 v13, v15, v13, v18
	v_alignbit_b32 v14, v19, v13, 9
	v_ffbh_u32_e32 v15, v14
	v_min_u32_e32 v15, 32, v15
	v_lshrrev_b32_e32 v21, 29, v17
	v_not_b32_e32 v18, v15
	v_alignbit_b32 v13, v14, v13, v18
	v_lshlrev_b32_e32 v14, 31, v21
	v_or_b32_e32 v18, 0x33000000, v14
	v_add_lshl_u32 v15, v15, v16, 23
	v_lshrrev_b32_e32 v13, 9, v13
	v_sub_u32_e32 v15, v18, v15
	v_or_b32_e32 v14, 0.5, v14
	v_lshlrev_b32_e32 v16, 23, v16
	v_or_b32_e32 v13, v15, v13
	v_lshrrev_b32_e32 v15, 9, v19
	v_sub_u32_e32 v14, v14, v16
	v_or_b32_e32 v14, v15, v14
	v_mul_f32_e32 v15, 0x3fc90fda, v14
	s_mov_b32 s0, 0x3fc90fda
	v_fma_f32 v16, v14, s0, -v15
	v_fmac_f32_e32 v16, 0x33a22168, v14
	v_fmac_f32_e32 v16, 0x3fc90fda, v13
	v_lshrrev_b32_e32 v14, 30, v17
	v_add_f32_e32 v13, v15, v16
	v_add_u32_e32 v14, v23, v14

; DI void sincos_(float x, float& sn, float& cs) { float s_, c_; sincosf(x, &s_, &c_); sn = s_; cs = c_; }
; DI void s5_fill(const Params& p, int j) {
;     ...
;     const float4 z = s5z[g * 64 + n];
;     const float d = (float)(31 - jj);
;     const float mg = expf(d * z.x), ang = d * z.y; float sn_, cs_; sincos_(ang, sn_, cs_);
;     const float er = mg * cs_, ei = mg * sn_;
;     const float2 bb = bbar[(g * 64 + n) * 16 + q];
;     const float v = (n2 < 64) ? (er * bb.x - ei * bb.y) : (er * bb.y + ei * bb.x);
;     WE[idx] = f2bf(v);
.Ls5f_tail1:
	s_or_b64 exec, exec, s[0:1]
	v_mul_f32_e32 v6, v4, v12
	v_mul_f32_e32 v4, v13, v13
	v_mul_f32_e32 v15, 0x3fb8aa3b, v6
	v_fmamk_f32 v18, v4, 0xb94c1982, v184
	v_fmamk_f32 v19, v4, 0x37d75334, v185
	v_fma_f32 v20, v6, s40, -v15
	v_rndne_f32_e32 v21, v15
	v_fmaak_f32 v18, v4, v18, 0xbe2aaa9d
	v_fmaak_f32 v19, v4, v19, 0x3d2aabf7
	v_fmac_f32_e32 v20, 0x32a5705f, v6
	v_sub_f32_e32 v15, v15, v21
	v_lshlrev_b32_e32 v12, 30, v14
	v_and_b32_e32 v14, 1, v14
	v_mul_f32_e32 v18, v4, v18
	v_fmaak_f32 v19, v4, v19, 0xbf000004
	v_add_f32_e32 v15, v15, v20
	v_cvt_i32_f32_e32 v21, v21
	v_fmac_f32_e32 v13, v13, v18
	v_fma_f32 v4, v4, v19, 1.0
	v_exp_f32_e32 v15, v15
	v_cmp_eq_u32_e32 vcc, 0, v14
	v_xor_b32_e32 v7, v7, v5
	v_and_b32_e32 v12, 0x80000000, v12
	v_cndmask_b32_e32 v14, v4, v13, vcc
	v_xor_b32_e32 v13, 0x80000000, v13
	v_xor_b32_e32 v7, v7, v14
	v_cndmask_b32_e32 v4, v13, v4, vcc
	s_movk_i32 s0, 0x1f8
	v_xor_b32_e32 v7, v7, v12
	v_xor_b32_e32 v4, v4, v12
	v_cmp_class_f32_e64 vcc, v5, s0
	s_nop 1
	v_cndmask_b32_e32 v5, v203, v7, vcc
	v_cndmask_b32_e32 v4, v203, v4, vcc
	v_ldexp_f32 v7, v15, v21
	v_cmp_ngt_f32_e32 vcc, s41, v6
	s_nop 1
	v_cndmask_b32_e32 v7, 0, v7, vcc
	v_cmp_nlt_f32_e32 vcc, s50, v6
	s_nop 1
	v_cndmask_b32_e32 v6, v202, v7, vcc
	v_pk_mul_f32 v[4:5], v[6:7], v[4:5] op_sel_hi:[0,1]
	s_waitcnt vmcnt(0)
	v_cmp_gt_u32_e32 vcc, 32, v8
	v_mul_f32_e32 v0, v32, v4
	v_mul_f32_e32 v1, v33, v5
	v_mul_f32_e32 v2, v33, v4
	v_mul_f32_e32 v3, v32, v5
	v_sub_f32_e32 v0, v0, v1
	v_add_f32_e32 v2, v2, v3
	v_cndmask_b32_e32 v64, v2, v0, vcc
	v_mul_f32_e32 v0, v34, v4
	v_mul_f32_e32 v1, v35, v5
	v_mul_f32_e32 v2, v35, v4
	v_mul_f32_e32 v3, v34, v5
	v_sub_f32_e32 v0, v0, v1
	v_add_f32_e32 v2, v2, v3
	v_cndmask_b32_e32 v65, v2, v0, vcc
	v_mul_f32_e32 v0, v36, v4
	v_mul_f32_e32 v1, v37, v5
	v_mul_f32_e32 v2, v37, v4
	v_mul_f32_e32 v3, v36, v5
	v_sub_f32_e32 v0, v0, v1
	v_add_f32_e32 v2, v2, v3
	v_cndmask_b32_e32 v66, v2, v0, vcc
	v_mul_f32_e32 v0, v38, v4
	v_mul_f32_e32 v1, v39, v5
	v_mul_f32_e32 v2, v39, v4
	v_mul_f32_e32 v3, v38, v5
	v_sub_f32_e32 v0, v0, v1
	v_add_f32_e32 v2, v2, v3
	v_cndmask_b32_e32 v67, v2, v0, vcc
	v_mul_f32_e32 v0, v40, v4
	v_mul_f32_e32 v1, v41, v5
	v_mul_f32_e32 v2, v41, v4
	v_mul_f32_e32 v3, v40, v5
	v_sub_f32_e32 v0, v0, v1
	v_add_f32_e32 v2, v2, v3
	v_cndmask_b32_e32 v68, v2, v0, vcc
	v_mul_f32_e32 v0, v42, v4
	v_mul_f32_e32 v1, v43, v5
	v_mul_f32_e32 v2, v43, v4
	v_mul_f32_e32 v3, v42, v5
	v_sub_f32_e32 v0, v0, v1
	v_add_f32_e32 v2, v2, v3
	v_cndmask_b32_e32 v69, v2, v0, vcc
	v_mul_f32_e32 v0, v44, v4
	v_mul_f32_e32 v1, v45, v5
	v_mul_f32_e32 v2, v45, v4
	v_mul_f32_e32 v3, v44, v5
	v_sub_f32_e32 v0, v0, v1
	v_add_f32_e32 v2, v2, v3
	v_cndmask_b32_e32 v70, v2, v0, vcc
	v_mul_f32_e32 v0, v46, v4
	v_mul_f32_e32 v1, v47, v5
	v_mul_f32_e32 v2, v47, v4
	v_mul_f32_e32 v3, v46, v5
	v_sub_f32_e32 v0, v0, v1
	v_add_f32_e32 v2, v2, v3
	v_cndmask_b32_e32 v71, v2, v0, vcc
	v_mul_f32_e32 v0, v48, v4
	v_mul_f32_e32 v1, v49, v5
	v_mul_f32_e32 v2, v49, v4
	v_mul_f32_e32 v3, v48, v5
	v_sub_f32_e32 v0, v0, v1
	v_add_f32_e32 v2, v2, v3
	v_cndmask_b32_e32 v72, v2, v0, vcc
	v_mul_f32_e32 v0, v50, v4
	v_mul_f32_e32 v1, v51, v5
	v_mul_f32_e32 v2, v51, v4
	v_mul_f32_e32 v3, v50, v5
	v_sub_f32_e32 v0, v0, v1
	v_add_f32_e32 v2, v2, v3
	v_cndmask_b32_e32 v73, v2, v0, vcc
	v_mul_f32_e32 v0, v52, v4
	v_mul_f32_e32 v1, v53, v5
	v_mul_f32_e32 v2, v53, v4
	v_mul_f32_e32 v3, v52, v5
	v_sub_f32_e32 v0, v0, v1
	v_add_f32_e32 v2, v2, v3
	v_cndmask_b32_e32 v74, v2, v0, vcc
	v_mul_f32_e32 v0, v54, v4
	v_mul_f32_e32 v1, v55, v5
	v_mul_f32_e32 v2, v55, v4
	v_mul_f32_e32 v3, v54, v5
	v_sub_f32_e32 v0, v0, v1
	v_add_f32_e32 v2, v2, v3
	v_cndmask_b32_e32 v75, v2, v0, vcc
	v_mul_f32_e32 v0, v56, v4
	v_mul_f32_e32 v1, v57, v5
	v_mul_f32_e32 v2, v57, v4
	v_mul_f32_e32 v3, v56, v5
	v_sub_f32_e32 v0, v0, v1
	v_add_f32_e32 v2, v2, v3
	v_cndmask_b32_e32 v76, v2, v0, vcc
	v_mul_f32_e32 v0, v58, v4
	v_mul_f32_e32 v1, v59, v5
	v_mul_f32_e32 v2, v59, v4
	v_mul_f32_e32 v3, v58, v5
	v_sub_f32_e32 v0, v0, v1
	v_add_f32_e32 v2, v2, v3
	v_cndmask_b32_e32 v77, v2, v0, vcc
	v_mul_f32_e32 v0, v60, v4
	v_mul_f32_e32 v1, v61, v5
	v_mul_f32_e32 v2, v61, v4
	v_mul_f32_e32 v3, v60, v5
	v_sub_f32_e32 v0, v0, v1
	v_add_f32_e32 v2, v2, v3
	v_cndmask_b32_e32 v78, v2, v0, vcc
	v_mul_f32_e32 v0, v62, v4
	v_mul_f32_e32 v1, v63, v5
	v_mul_f32_e32 v2, v63, v4
	v_mul_f32_e32 v3, v62, v5
	v_sub_f32_e32 v0, v0, v1
	v_add_f32_e32 v2, v2, v3
	v_cndmask_b32_e32 v79, v2, v0, vcc
	v_cvt_pk_bf16_f32 v80, v64, v65
	v_cvt_pk_bf16_f32 v81, v66, v67
	v_cvt_pk_bf16_f32 v82, v68, v69
	v_cvt_pk_bf16_f32 v83, v70, v71
	v_cvt_pk_bf16_f32 v84, v72, v73
	v_cvt_pk_bf16_f32 v85, v74, v75
	v_cvt_pk_bf16_f32 v86, v76, v77
	v_cvt_pk_bf16_f32 v87, v78, v79
	s_lshr_b32 s0, s34, 6
	s_lshl_b32 s0, s0, 8
	s_and_b32 s1, s34, 63
	s_add_u32 s0, s0, s1
	s_lshl_b32 s0, s0, 10
	s_add_u32 s78, s14, s0
	s_addc_u32 s79, s15, 0
	v_lshlrev_b32_e32 v0, 16, v10
	v_lshl_add_u32 v0, v9, 5, v0
	global_store_dwordx4 v0, v[80:83], s[78:79]
	global_store_dwordx4 v0, v[84:87], s[78:79] offset:16
	s_add_u32 s34, s34, s35
	s_branch .Ls5f_e_loop

; DI void sincos_(float x, float& sn, float& cs) { float s_, c_; sincosf(x, &s_, &c_); sn = s_; cs = c_; }
; DI void s5_fill(const Params& p, int j) {
;     ...
;   for (int idx = bid * NTHR + tid; idx < 32 * 512 * 640; idx += nb * NTHR) {
;     const int g = idx / (512 * 640), rem = idx - g * (512 * 640), mrow = rem / 640, k = rem - mrow * 640;
;     const int i = mrow >> 4, pp = mrow & 15;
;     float v;
;     if (k < 512) {
;       const int jj = k >> 4, q = k & 15, d = i - jj;
;       v = (d >= 0) ? ktab[(g * 32 + d) * 256 + pp * 16 + q] : 0.f;
;       if (d == 0 && q == pp) v += p.s5_d[j * 512 + g * 16 + pp];
;     } else {
;       const int n2 = k - 512, n = n2 & 63;
;       const float4 z = s5z[g * 64 + n];
;       const float d = (float)(i + 1);
;       const float mg = expf(d * z.x), ang = d * z.y; float sn_, cs_; sincos_(ang, sn_, cs_);
;     const float er = mg * cs_, ei = mg * sn_;
;       const float cr = p.s5_c_re[((j * 32 + g) * 16 + pp) * 64 + n], ci = p.s5_c_im[((j * 32 + g) * 16 + pp) * 64 + n];
;       v = (n2 < 64) ? (cr * er - ci * ei) : -(cr * ei + ci * er);
;     }
.Ls5f_y_loop:
	s_cmp_lt_u32 s34, 0x800
	s_cbranch_scc0 .Ls5f_y_done
	s_lshr_b32 s80, s34, 6
	s_bfe_u32 s81, s34, 0x50001
	s_and_b32 s82, s34, 1
	s_lshl_b32 s0, s80, 10
	s_add_u32 s0, s8, s0
	s_addc_u32 s1, s9, 0
	global_load_dwordx2 v[4:5], v11, s[0:1]
	s_lshl_b32 s0, s80, 4
	s_lshl_b32 s1, s82, 3
	s_add_u32 s0, s0, s1
	s_lshl_b32 s83, s0, 2
	s_lshl_b32 s0, s0, 8
	s_add_u32 s78, s24, s0
	s_addc_u32 s79, s25, 0
	s_add_u32 s0, s28, s0
	s_addc_u32 s1, s29, 0
	v_lshlrev_b32_e32 v0, 2, v8
	global_load_dword v32, v0, s[78:79]
	global_load_dword v33, v0, s[78:79] offset:256
	global_load_dword v34, v0, s[78:79] offset:512
	global_load_dword v35, v0, s[78:79] offset:768
	global_load_dword v36, v0, s[78:79] offset:1024
	global_load_dword v37, v0, s[78:79] offset:1280
	global_load_dword v38, v0, s[78:79] offset:1536
	global_load_dword v39, v0, s[78:79] offset:1792
	global_load_dword v40, v0, s[0:1]
	global_load_dword v41, v0, s[0:1] offset:256
	global_load_dword v42, v0, s[0:1] offset:512
	global_load_dword v43, v0, s[0:1] offset:768
	global_load_dword v44, v0, s[0:1] offset:1024
	global_load_dword v45, v0, s[0:1] offset:1280
	global_load_dword v46, v0, s[0:1] offset:1536
	global_load_dword v47, v0, s[0:1] offset:1792
	s_add_u32 s4, s76, s83
	s_addc_u32 s5, s77, 0
	s_load_dwordx8 s[68:75], s[4:5], 0x0
	s_add_u32 s0, s81, 1
	v_cvt_f32_u32_e32 v12, s0
	s_waitcnt vmcnt(16)
	v_mul_f32_e32 v5, v5, v12
	v_and_b32_e32 v7, 0x7fffffff, v5
	s_brev_b32 s0, 18
	v_cmp_nlt_f32_e64 s[0:1], |v5|, s0
	s_and_saveexec_b64 s[4:5], s[0:1]
	s_xor_b64 s[30:31], exec, s[4:5]
	s_cbranch_execz .Ls5f_small2
	v_lshrrev_b32_e32 v13, 23, v7
	v_add_u32_e32 v13, 0xffffff88, v13
	v_cmp_lt_u32_e32 vcc, 63, v13
	s_mov_b32 s6, 0xfe5163ab
	s_nop 0
	v_cndmask_b32_e32 v14, 0, v192, vcc
	v_add_u32_e32 v13, v14, v13
	v_cmp_lt_u32_e64 s[0:1], 31, v13
	s_nop 1
	v_cndmask_b32_e64 v14, 0, v201, s[0:1]
	v_add_u32_e32 v13, v14, v13
	v_cmp_lt_u32_e64 s[4:5], 31, v13
	s_nop 1
	v_cndmask_b32_e64 v14, 0, v201, s[4:5]
	v_add_u32_e32 v13, v14, v13
	v_and_b32_e32 v14, 0x7fffff, v7
	v_or_b32_e32 v26, 0x800000, v14
	v_mad_u64_u32 v[14:15], s[6:7], v26, s6, 0
	v_mov_b32_e32 v160, v15
	s_mov_b32 s6, 0x3c439041
	v_mad_u64_u32 v[16:17], s[6:7], v26, s6, v[160:161]
	v_mov_b32_e32 v160, v17
	s_mov_b32 s6, 0xdb629599
	v_mad_u64_u32 v[18:19], s[6:7], v26, s6, v[160:161]
	v_mov_b32_e32 v160, v19
	s_mov_b32 s6, 0xf534ddc0
	v_mad_u64_u32 v[20:21], s[6:7], v26, s6, v[160:161]
	v_mov_b32_e32 v160, v21
	s_mov_b32 s6, 0xfc2757d1
	v_mad_u64_u32 v[22:23], s[6:7], v26, s6, v[160:161]
	v_mov_b32_e32 v160, v23
	s_mov_b32 s6, 0x4e441529
	v_mad_u64_u32 v[24:25], s[6:7], v26, s6, v[160:161]
	v_mov_b32_e32 v160, v25
	s_mov_b32 s6, 0xa2f9836e
	v_mad_u64_u32 v[26:27], s[6:7], v26, s6, v[160:161]
	v_cndmask_b32_e32 v15, v24, v20, vcc
	v_cndmask_b32_e32 v17, v26, v22, vcc
	v_cndmask_b32_e32 v21, v27, v24, vcc
	v_cndmask_b32_e64 v19, v17, v15, s[0:1]
	v_cndmask_b32_e64 v17, v21, v17, s[0:1]
	v_cndmask_b32_e32 v21, v22, v18, vcc
	v_cndmask_b32_e64 v15, v15, v21, s[0:1]
	v_sub_u32_e32 v22, 32, v13
	v_cmp_eq_u32_e64 s[6:7], 0, v13
	v_cndmask_b32_e32 v13, v20, v16, vcc
	v_cndmask_b32_e64 v17, v17, v19, s[4:5]
	v_cndmask_b32_e64 v19, v19, v15, s[4:5]
	v_cndmask_b32_e64 v16, v21, v13, s[0:1]
	v_alignbit_b32 v23, v17, v19, v22
	v_cndmask_b32_e64 v15, v15, v16, s[4:5]
	v_cndmask_b32_e64 v17, v23, v17, s[6:7]
	v_alignbit_b32 v20, v19, v15, v22
	v_cndmask_b32_e32 v14, v18, v14, vcc
	v_cndmask_b32_e64 v19, v20, v19, s[6:7]
	v_bfe_u32 v23, v17, 29, 1
	v_cndmask_b32_e64 v13, v13, v14, s[0:1]
	v_alignbit_b32 v20, v17, v19, 30
	v_sub_u32_e32 v24, 0, v23
	v_cndmask_b32_e64 v13, v16, v13, s[4:5]
	v_xor_b32_e32 v20, v20, v24
	v_alignbit_b32 v14, v15, v13, v22
	v_cndmask_b32_e64 v14, v14, v15, s[6:7]
	v_ffbh_u32_e32 v16, v20
	v_alignbit_b32 v15, v19, v14, 30
	v_min_u32_e32 v16, 32, v16
	v_alignbit_b32 v13, v14, v13, 30
	v_xor_b32_e32 v15, v15, v24
	v_sub_u32_e32 v18, 31, v16
	v_xor_b32_e32 v13, v13, v24
	v_alignbit_b32 v19, v20, v15, v18
	v_alignbit_b32 v13, v15, v13, v18
	v_alignbit_b32 v14, v19, v13, 9
	v_ffbh_u32_e32 v15, v14
	v_min_u32_e32 v15, 32, v15
	v_lshrrev_b32_e32 v21, 29, v17
	v_not_b32_e32 v18, v15
	v_alignbit_b32 v13, v14, v13, v18
	v_lshlrev_b32_e32 v14, 31, v21
	v_or_b32_e32 v18, 0x33000000, v14
	v_add_lshl_u32 v15, v15, v16, 23
	v_lshrrev_b32_e32 v13, 9, v13
	v_sub_u32_e32 v15, v18, v15
	v_or_b32_e32 v14, 0.5, v14
	v_lshlrev_b32_e32 v16, 23, v16
	v_or_b32_e32 v13, v15, v13
	v_lshrrev_b32_e32 v15, 9, v19
	v_sub_u32_e32 v14, v14, v16
	v_or_b32_e32 v14, v15, v14
	v_mul_f32_e32 v15, 0x3fc90fda, v14
	s_mov_b32 s0, 0x3fc90fda
	v_fma_f32 v16, v14, s0, -v15
	v_fmac_f32_e32 v16, 0x33a22168, v14
	v_fmac_f32_e32 v16, 0x3fc90fda, v13
	v_lshrrev_b32_e32 v14, 30, v17
	v_add_f32_e32 v13, v15, v16
	v_add_u32_e32 v14, v23, v14

; DI void sincos_(float x, float& sn, float& cs) { float s_, c_; sincosf(x, &s_, &c_); sn = s_; cs = c_; }
; DI void s5_fill(const Params& p, int j) {
;     ...
;   for (int idx = bid * NTHR + tid; idx < 32 * 512 * 640; idx += nb * NTHR) {
;     const int g = idx / (512 * 640), rem = idx - g * (512 * 640), mrow = rem / 640, k = rem - mrow * 640;
;     const int i = mrow >> 4, pp = mrow & 15;
;     float v;
;     if (k < 512) {
;       const int jj = k >> 4, q = k & 15, d = i - jj;
;       v = (d >= 0) ? ktab[(g * 32 + d) * 256 + pp * 16 + q] : 0.f;
;       if (d == 0 && q == pp) v += p.s5_d[j * 512 + g * 16 + pp];
;     } else {
;       const int n2 = k - 512, n = n2 & 63;
;       const float4 z = s5z[g * 64 + n];
;       const float d = (float)(i + 1);
;       const float mg = expf(d * z.x), ang = d * z.y; float sn_, cs_; sincos_(ang, sn_, cs_);
;     const float er = mg * cs_, ei = mg * sn_;
;       const float cr = p.s5_c_re[((j * 32 + g) * 16 + pp) * 64 + n], ci = p.s5_c_im[((j * 32 + g) * 16 + pp) * 64 + n];
;       v = (n2 < 64) ? (cr * er - ci * ei) : -(cr * ei + ci * er);
;     }
;     WY[idx] = f2bf(v);
.Ls5f_tail2:
	s_or_b64 exec, exec, s[0:1]
	v_mul_f32_e32 v6, v4, v12
	v_mul_f32_e32 v4, v13, v13
	v_mul_f32_e32 v15, 0x3fb8aa3b, v6
	v_fmamk_f32 v18, v4, 0xb94c1982, v184
	v_fmamk_f32 v19, v4, 0x37d75334, v185
	v_fma_f32 v20, v6, s40, -v15
	v_rndne_f32_e32 v21, v15
	v_fmaak_f32 v18, v4, v18, 0xbe2aaa9d
	v_fmaak_f32 v19, v4, v19, 0x3d2aabf7
	v_fmac_f32_e32 v20, 0x32a5705f, v6
	v_sub_f32_e32 v15, v15, v21
	v_lshlrev_b32_e32 v12, 30, v14
	v_and_b32_e32 v14, 1, v14
	v_mul_f32_e32 v18, v4, v18
	v_fmaak_f32 v19, v4, v19, 0xbf000004
	v_add_f32_e32 v15, v15, v20
	v_cvt_i32_f32_e32 v21, v21
	v_fmac_f32_e32 v13, v13, v18
	v_fma_f32 v4, v4, v19, 1.0
	v_exp_f32_e32 v15, v15
	v_cmp_eq_u32_e32 vcc, 0, v14
	v_xor_b32_e32 v7, v7, v5
	v_and_b32_e32 v12, 0x80000000, v12
	v_cndmask_b32_e32 v14, v4, v13, vcc
	v_xor_b32_e32 v13, 0x80000000, v13
	v_xor_b32_e32 v7, v7, v14
	v_cndmask_b32_e32 v4, v13, v4, vcc
	s_movk_i32 s0, 0x1f8
	v_xor_b32_e32 v7, v7, v12
	v_xor_b32_e32 v4, v4, v12
	v_cmp_class_f32_e64 vcc, v5, s0
	s_nop 1
	v_cndmask_b32_e32 v5, v203, v7, vcc
	v_cndmask_b32_e32 v4, v203, v4, vcc
	v_ldexp_f32 v7, v15, v21
	v_cmp_ngt_f32_e32 vcc, s41, v6
	s_nop 1
	v_cndmask_b32_e32 v7, 0, v7, vcc
	v_cmp_nlt_f32_e32 vcc, s50, v6
	s_nop 1
	v_cndmask_b32_e32 v6, v202, v7, vcc
	v_pk_mul_f32 v[4:5], v[6:7], v[4:5] op_sel_hi:[0,1]
	s_lshl_b32 s0, s80, 9
	s_lshl_b32 s1, s81, 4
	s_add_u32 s0, s0, s1
	s_lshl_b32 s1, s82, 3
	s_add_u32 s0, s0, s1
	s_mul_i32 s0, s0, 0x500
	s_add_u32 s78, s10, s0
	s_addc_u32 s79, s11, 0
	s_mov_b64 s[26:27], s[78:79]
	v_lshlrev_b32_e32 v0, 1, v8
	s_waitcnt vmcnt(0)
	v_mul_f32_e32 v1, v40, v5
	v_fma_f32 v1, v32, v4, -v1
	v_mul_f32_e32 v2, v32, v5
	v_fmac_f32_e32 v2, v40, v4
	v_xor_b32_e32 v2, 0x80000000, v2
	v_cvt_pk_bf16_f32 v1, v1, v1
	v_cvt_pk_bf16_f32 v2, v2, v2
	global_store_short v0, v1, s[26:27] offset:1024
	global_store_short v0, v2, s[26:27] offset:1152
	s_add_u32 s26, s26, 0x500
	s_addc_u32 s27, s27, 0
	v_mul_f32_e32 v1, v41, v5
	v_fma_f32 v1, v33, v4, -v1
	v_mul_f32_e32 v2, v33, v5
	v_fmac_f32_e32 v2, v41, v4
	v_xor_b32_e32 v2, 0x80000000, v2
	v_cvt_pk_bf16_f32 v1, v1, v1
	v_cvt_pk_bf16_f32 v2, v2, v2
	global_store_short v0, v1, s[26:27] offset:1024
	global_store_short v0, v2, s[26:27] offset:1152
	s_add_u32 s26, s26, 0x500
	s_addc_u32 s27, s27, 0
	v_mul_f32_e32 v1, v42, v5
	v_fma_f32 v1, v34, v4, -v1
	v_mul_f32_e32 v2, v34, v5
	v_fmac_f32_e32 v2, v42, v4
	v_xor_b32_e32 v2, 0x80000000, v2
	v_cvt_pk_bf16_f32 v1, v1, v1
	v_cvt_pk_bf16_f32 v2, v2, v2
	global_store_short v0, v1, s[26:27] offset:1024
	global_store_short v0, v2, s[26:27] offset:1152
	s_add_u32 s26, s26, 0x500
	s_addc_u32 s27, s27, 0
	v_mul_f32_e32 v1, v43, v5
	v_fma_f32 v1, v35, v4, -v1
	v_mul_f32_e32 v2, v35, v5
	v_fmac_f32_e32 v2, v43, v4
	v_xor_b32_e32 v2, 0x80000000, v2
	v_cvt_pk_bf16_f32 v1, v1, v1
	v_cvt_pk_bf16_f32 v2, v2, v2
	global_store_short v0, v1, s[26:27] offset:1024
	global_store_short v0, v2, s[26:27] offset:1152
	s_add_u32 s26, s26, 0x500
	s_addc_u32 s27, s27, 0
	v_mul_f32_e32 v1, v44, v5
	v_fma_f32 v1, v36, v4, -v1
	v_mul_f32_e32 v2, v36, v5
	v_fmac_f32_e32 v2, v44, v4
	v_xor_b32_e32 v2, 0x80000000, v2
	v_cvt_pk_bf16_f32 v1, v1, v1
	v_cvt_pk_bf16_f32 v2, v2, v2
	global_store_short v0, v1, s[26:27] offset:1024
	global_store_short v0, v2, s[26:27] offset:1152
	s_add_u32 s26, s26, 0x500
	s_addc_u32 s27, s27, 0
	v_mul_f32_e32 v1, v45, v5
	v_fma_f32 v1, v37, v4, -v1
	v_mul_f32_e32 v2, v37, v5
	v_fmac_f32_e32 v2, v45, v4
	v_xor_b32_e32 v2, 0x80000000, v2
	v_cvt_pk_bf16_f32 v1, v1, v1
	v_cvt_pk_bf16_f32 v2, v2, v2
	global_store_short v0, v1, s[26:27] offset:1024
	global_store_short v0, v2, s[26:27] offset:1152
	s_add_u32 s26, s26, 0x500
	s_addc_u32 s27, s27, 0
	v_mul_f32_e32 v1, v46, v5
	v_fma_f32 v1, v38, v4, -v1
	v_mul_f32_e32 v2, v38, v5
	v_fmac_f32_e32 v2, v46, v4
	v_xor_b32_e32 v2, 0x80000000, v2
	v_cvt_pk_bf16_f32 v1, v1, v1
	v_cvt_pk_bf16_f32 v2, v2, v2
	global_store_short v0, v1, s[26:27] offset:1024
	global_store_short v0, v2, s[26:27] offset:1152
	s_add_u32 s26, s26, 0x500
	s_addc_u32 s27, s27, 0
	v_mul_f32_e32 v1, v47, v5
	v_fma_f32 v1, v39, v4, -v1
	v_mul_f32_e32 v2, v39, v5
	v_fmac_f32_e32 v2, v47, v4
	v_xor_b32_e32 v2, 0x80000000, v2
	v_cvt_pk_bf16_f32 v1, v1, v1
	v_cvt_pk_bf16_f32 v2, v2, v2
	global_store_short v0, v1, s[26:27] offset:1024
	global_store_short v0, v2, s[26:27] offset:1152
	v_mov_b32_e32 v32, 0
	v_mov_b32_e32 v33, 0
	v_mov_b32_e32 v34, 0
	v_mov_b32_e32 v35, 0
	v_mov_b32_e32 v36, 0
	v_mov_b32_e32 v37, 0
	v_mov_b32_e32 v38, 0
	v_mov_b32_e32 v39, 0
	v_mov_b32_e32 v40, 0
	v_mov_b32_e32 v41, 0
	v_mov_b32_e32 v42, 0
	v_mov_b32_e32 v43, 0
	v_mov_b32_e32 v44, 0
; DI void s5_fill(const Params& p, int j) {
;     ...
;     if (k < 512) {
;       const int jj = k >> 4, q = k & 15, d = i - jj;
;       v = (d >= 0) ? ktab[(g * 32 + d) * 256 + pp * 16 + q] : 0.f;
;       if (d == 0 && q == pp) v += p.s5_d[j * 512 + g * 16 + pp];
;     ...
;     WY[idx] = f2bf(v);
	v_mov_b32_e32 v45, 0
	v_mov_b32_e32 v46, 0
	v_mov_b32_e32 v47, 0
	v_mov_b32_e32 v48, 0
	v_mov_b32_e32 v49, 0
	v_mov_b32_e32 v50, 0
	v_mov_b32_e32 v51, 0
	v_mov_b32_e32 v52, 0
	v_mov_b32_e32 v53, 0
	v_mov_b32_e32 v54, 0
	v_mov_b32_e32 v55, 0
	v_mov_b32_e32 v56, 0
	v_mov_b32_e32 v57, 0
	v_mov_b32_e32 v58, 0
	v_mov_b32_e32 v59, 0
	v_mov_b32_e32 v60, 0
	v_mov_b32_e32 v61, 0
	v_mov_b32_e32 v62, 0
	v_mov_b32_e32 v63, 0
	v_mov_b32_e32 v64, 0
	v_mov_b32_e32 v65, 0
	v_mov_b32_e32 v66, 0
	v_mov_b32_e32 v67, 0
	v_mov_b32_e32 v68, 0
	v_mov_b32_e32 v69, 0
	v_mov_b32_e32 v70, 0
	v_mov_b32_e32 v71, 0
	v_mov_b32_e32 v72, 0
	v_mov_b32_e32 v73, 0
	v_mov_b32_e32 v74, 0
	v_mov_b32_e32 v75, 0
	v_mov_b32_e32 v76, 0
	v_mov_b32_e32 v77, 0
	v_mov_b32_e32 v78, 0
	v_mov_b32_e32 v79, 0
	v_mov_b32_e32 v80, 0
	v_mov_b32_e32 v81, 0
	v_mov_b32_e32 v82, 0
	v_mov_b32_e32 v83, 0
	v_mov_b32_e32 v84, 0
	v_mov_b32_e32 v85, 0
	v_mov_b32_e32 v86, 0
	v_mov_b32_e32 v87, 0
	v_mov_b32_e32 v88, 0
	v_mov_b32_e32 v89, 0
	v_mov_b32_e32 v90, 0
	v_mov_b32_e32 v91, 0
	v_mov_b32_e32 v92, 0
	v_mov_b32_e32 v93, 0
	v_mov_b32_e32 v94, 0
	v_mov_b32_e32 v95, 0
	v_lshrrev_b32_e32 v1, 1, v8
	v_and_b32_e32 v2, 1, v8
	v_sub_u32_e32 v1, s81, v1
	v_lshlrev_b32_e32 v3, 10, v1
	v_lshl_add_u32 v3, v2, 5, v3
	s_lshl_b32 s0, s80, 15
	s_lshl_b32 s1, s82, 9
	s_add_u32 s0, s0, s1
	s_add_u32 s0, s22, s0
	s_addc_u32 s1, s23, 0
	v_cmp_le_i32_e32 vcc, 0, v1
	s_and_saveexec_b64 s[26:27], vcc
	global_load_dwordx4 v[32:35], v3, s[0:1] offset:0
	global_load_dwordx4 v[36:39], v3, s[0:1] offset:16
	global_load_dwordx4 v[40:43], v3, s[0:1] offset:64
	global_load_dwordx4 v[44:47], v3, s[0:1] offset:80
	global_load_dwordx4 v[48:51], v3, s[0:1] offset:128
	global_load_dwordx4 v[52:55], v3, s[0:1] offset:144
	global_load_dwordx4 v[56:59], v3, s[0:1] offset:192
	global_load_dwordx4 v[60:63], v3, s[0:1] offset:208
	global_load_dwordx4 v[64:67], v3, s[0:1] offset:256
	global_load_dwordx4 v[68:71], v3, s[0:1] offset:272
	global_load_dwordx4 v[72:75], v3, s[0:1] offset:320
	global_load_dwordx4 v[76:79], v3, s[0:1] offset:336
	global_load_dwordx4 v[80:83], v3, s[0:1] offset:384
	global_load_dwordx4 v[84:87], v3, s[0:1] offset:400
	global_load_dwordx4 v[88:91], v3, s[0:1] offset:448
	global_load_dwordx4 v[92:95], v3, s[0:1] offset:464
	s_mov_b64 exec, s[26:27]
	v_cmp_eq_u32_e32 vcc, 0, v1
	v_cmp_eq_u32_e64 s[4:5], s82, v2
	s_and_b64 s[4:5], s[4:5], vcc
	s_waitcnt vmcnt(0) lgkmcnt(0)
	s_and_saveexec_b64 s[26:27], s[4:5]
	v_add_f32_e32 v32, s68, v32
	v_add_f32_e32 v41, s69, v41
	v_add_f32_e32 v50, s70, v50
	v_add_f32_e32 v59, s71, v59
	v_add_f32_e32 v68, s72, v68
	v_add_f32_e32 v77, s73, v77
	v_add_f32_e32 v86, s74, v86
	v_add_f32_e32 v95, s75, v95
	s_mov_b64 exec, s[26:27]
	v_cvt_pk_bf16_f32 v96, v32, v33
	v_cvt_pk_bf16_f32 v97, v34, v35
	v_cvt_pk_bf16_f32 v98, v36, v37
	v_cvt_pk_bf16_f32 v99, v38, v39
	global_store_dwordx4 v11, v[96:99], s[78:79]
	s_add_u32 s78, s78, 0x500
	s_addc_u32 s79, s79, 0
	v_cvt_pk_bf16_f32 v100, v40, v41
	v_cvt_pk_bf16_f32 v101, v42, v43
	v_cvt_pk_bf16_f32 v102, v44, v45
	v_cvt_pk_bf16_f32 v103, v46, v47
	global_store_dwordx4 v11, v[100:103], s[78:79]
	s_add_u32 s78, s78, 0x500
	s_addc_u32 s79, s79, 0
	v_cvt_pk_bf16_f32 v96, v48, v49
	v_cvt_pk_bf16_f32 v97, v50, v51
	v_cvt_pk_bf16_f32 v98, v52, v53
	v_cvt_pk_bf16_f32 v99, v54, v55
	global_store_dwordx4 v11, v[96:99], s[78:79]
	s_add_u32 s78, s78, 0x500
	s_addc_u32 s79, s79, 0
	v_cvt_pk_bf16_f32 v100, v56, v57
	v_cvt_pk_bf16_f32 v101, v58, v59
	v_cvt_pk_bf16_f32 v102, v60, v61
	v_cvt_pk_bf16_f32 v103, v62, v63
	global_store_dwordx4 v11, v[100:103], s[78:79]
	s_add_u32 s78, s78, 0x500
	s_addc_u32 s79, s79, 0
	v_cvt_pk_bf16_f32 v96, v64, v65
	v_cvt_pk_bf16_f32 v97, v66, v67
	v_cvt_pk_bf16_f32 v98, v68, v69
	v_cvt_pk_bf16_f32 v99, v70, v71
	global_store_dwordx4 v11, v[96:99], s[78:79]
	s_add_u32 s78, s78, 0x500
	s_addc_u32 s79, s79, 0
	v_cvt_pk_bf16_f32 v100, v72, v73
	v_cvt_pk_bf16_f32 v101, v74, v75
	v_cvt_pk_bf16_f32 v102, v76, v77
	v_cvt_pk_bf16_f32 v103, v78, v79
	global_store_dwordx4 v11, v[100:103], s[78:79]
	s_add_u32 s78, s78, 0x500
	s_addc_u32 s79, s79, 0
	v_cvt_pk_bf16_f32 v96, v80, v81
	v_cvt_pk_bf16_f32 v97, v82, v83
	v_cvt_pk_bf16_f32 v98, v84, v85
	v_cvt_pk_bf16_f32 v99, v86, v87
	global_store_dwordx4 v11, v[96:99], s[78:79]
	s_add_u32 s78, s78, 0x500
	s_addc_u32 s79, s79, 0
	v_cvt_pk_bf16_f32 v100, v88, v89
	v_cvt_pk_bf16_f32 v101, v90, v91
	v_cvt_pk_bf16_f32 v102, v92, v93
	v_cvt_pk_bf16_f32 v103, v94, v95
	global_store_dwordx4 v11, v[100:103], s[78:79]
	s_add_u32 s34, s34, s35
	s_branch .Ls5f_y_loop
.Ls5f_y_done:
	s_mov_b32 s85, 0x3fb8aa3b
.LBB0_846:
	s_mov_b64 s[4:5], 0
